# adaLN GEMV software-pipelined across items: next item's first six weight loads issued before the cross-wave reduction and its barriers
# speedup vs baseline: 1.0056x; 1.0010x over previous
.LBB0_24:
	s_or_b64 exec, exec, s[6:7]
	s_add_i32 s8, s8, s34
	s_cmpk_lt_i32 s8, 0x300
	s_barrier
	s_cbranch_scc0 .LBB0_29
	s_mul_hi_i32 s0, s8, 0x2aaaaaab
	s_lshr_b32 s1, s0, 31
	s_ashr_i32 s5, s0, 5
	s_add_i32 s5, s5, s1
	s_mul_i32 s0, s5, 0xc0
	s_sub_i32 s0, s8, s0
	s_lshl_b32 s4, s0, 6
	s_branch .Lada_part_b

.Lada_part_b:
	v_or_b32_e32 v0, 6, v13
	v_lshl_add_u32 v89, v13, 2, 0
	v_mad_i64_i32 v[0:1], s[0:1], v0, s3, v[6:7]
	ds_read_b128 v[38:41], v89
	ds_read_b128 v[42:45], v89 offset:16
	global_load_dwordx4 v[46:49], v[0:1], off nt
	v_or_b32_e32 v2, 7, v13
	v_or_b32_e32 v3, 8, v13
	v_or_b32_e32 v74, 9, v13
	ds_read_b128 v[50:53], v89 offset:8192
	ds_read_b128 v[54:57], v89 offset:8208
	ds_read_b128 v[58:61], v89 offset:16384
	ds_read_b128 v[62:65], v89 offset:16400
	ds_read_b128 v[66:69], v89 offset:24576
	ds_read_b128 v[70:73], v89 offset:24592
	v_mad_i64_i32 v[82:83], s[0:1], v2, s3, v[6:7]
	v_mad_i64_i32 v[84:85], s[0:1], v3, s3, v[6:7]
	v_mad_i64_i32 v[86:87], s[0:1], v74, s3, v[6:7]
	global_load_dwordx4 v[74:77], v[82:83], off nt
	global_load_dwordx4 v[78:81], v[84:85], off nt
	global_load_dwordx4 v[0:3], v[86:87], off nt
	s_waitcnt lgkmcnt(7)
	v_mov_b32_e32 v88, v41
	s_waitcnt lgkmcnt(5)
	v_mov_b32_e32 v90, v53
	s_waitcnt lgkmcnt(3)
	v_mov_b32_e32 v92, v61
	s_waitcnt lgkmcnt(1)
	v_mov_b32_e32 v94, v69
	s_waitcnt vmcnt(9)
	v_pk_fma_f32 v[82:83], v[16:17], v[38:39], 0 op_sel_hi:[1,0,0]
	v_pk_fma_f32 v[84:85], v[14:15], v[38:39], 0 op_sel_hi:[1,0,0]
	v_pk_fma_f32 v[86:87], v[16:17], v[50:51], 0 op_sel_hi:[1,0,0]
	v_pk_fma_f32 v[96:97], v[14:15], v[50:51], 0 op_sel_hi:[1,0,0]
	v_pk_fma_f32 v[98:99], v[16:17], v[58:59], 0 op_sel_hi:[1,0,0]
	v_pk_fma_f32 v[100:101], v[14:15], v[58:59], 0 op_sel_hi:[1,0,0]
	v_pk_fma_f32 v[14:15], v[14:15], v[66:67], 0 op_sel_hi:[1,0,0]
	v_pk_fma_f32 v[16:17], v[16:17], v[66:67], 0 op_sel_hi:[1,0,0]
	s_waitcnt vmcnt(8)
	v_pk_fma_f32 v[82:83], v[20:21], v[38:39], v[82:83] op_sel:[0,1,0]
	v_pk_fma_f32 v[38:39], v[18:19], v[38:39], v[84:85] op_sel:[0,1,0]
	v_pk_fma_f32 v[84:85], v[20:21], v[50:51], v[86:87] op_sel:[0,1,0]
	v_pk_fma_f32 v[50:51], v[18:19], v[50:51], v[96:97] op_sel:[0,1,0]
	v_pk_fma_f32 v[86:87], v[20:21], v[58:59], v[98:99] op_sel:[0,1,0]
	v_pk_fma_f32 v[58:59], v[18:19], v[58:59], v[100:101] op_sel:[0,1,0]
	v_pk_fma_f32 v[14:15], v[18:19], v[66:67], v[14:15] op_sel:[0,1,0]
	v_pk_fma_f32 v[16:17], v[20:21], v[66:67], v[16:17] op_sel:[0,1,0]
	s_waitcnt vmcnt(7)
	v_pk_fma_f32 v[18:19], v[24:25], v[40:41], v[82:83] op_sel_hi:[1,0,1]
	v_pk_fma_f32 v[20:21], v[22:23], v[40:41], v[38:39] op_sel_hi:[1,0,1]
	v_pk_fma_f32 v[38:39], v[24:25], v[52:53], v[84:85] op_sel_hi:[1,0,1]
	v_pk_fma_f32 v[40:41], v[22:23], v[52:53], v[50:51] op_sel_hi:[1,0,1]
	v_pk_fma_f32 v[52:53], v[22:23], v[60:61], v[58:59] op_sel_hi:[1,0,1]
	v_pk_fma_f32 v[14:15], v[22:23], v[68:69], v[14:15] op_sel_hi:[1,0,1]
	v_pk_fma_f32 v[50:51], v[24:25], v[60:61], v[86:87] op_sel_hi:[1,0,1]
	v_pk_fma_f32 v[16:17], v[24:25], v[68:69], v[16:17] op_sel_hi:[1,0,1]
	s_waitcnt vmcnt(6)
	v_pk_fma_f32 v[18:19], v[28:29], v[88:89], v[18:19] op_sel_hi:[1,0,1]
	v_pk_fma_f32 v[20:21], v[26:27], v[88:89], v[20:21] op_sel_hi:[1,0,1]
	v_pk_fma_f32 v[22:23], v[28:29], v[90:91], v[38:39] op_sel_hi:[1,0,1]
	v_pk_fma_f32 v[24:25], v[26:27], v[90:91], v[40:41] op_sel_hi:[1,0,1]
	v_pk_fma_f32 v[40:41], v[26:27], v[92:93], v[52:53] op_sel_hi:[1,0,1]
	v_pk_fma_f32 v[26:27], v[26:27], v[94:95], v[14:15] op_sel_hi:[1,0,1]
	v_or_b32_e32 v14, 10, v13
	v_pk_fma_f32 v[38:39], v[28:29], v[92:93], v[50:51] op_sel_hi:[1,0,1]
	v_pk_fma_f32 v[28:29], v[28:29], v[94:95], v[16:17] op_sel_hi:[1,0,1]
	s_waitcnt vmcnt(5)
	v_pk_fma_f32 v[50:51], v[32:33], v[42:43], v[18:19] op_sel_hi:[1,0,1]
	v_mad_i64_i32 v[14:15], s[0:1], v14, s3, v[6:7]
	v_pk_fma_f32 v[52:53], v[30:31], v[42:43], v[20:21] op_sel_hi:[1,0,1]
	v_pk_fma_f32 v[22:23], v[32:33], v[54:55], v[22:23] op_sel_hi:[1,0,1]
	v_or_b32_e32 v18, 11, v13
	global_load_dwordx4 v[14:17], v[14:15], off nt
	v_pk_fma_f32 v[24:25], v[30:31], v[54:55], v[24:25] op_sel_hi:[1,0,1]
	v_pk_fma_f32 v[38:39], v[32:33], v[62:63], v[38:39] op_sel_hi:[1,0,1]
	v_pk_fma_f32 v[40:41], v[30:31], v[62:63], v[40:41] op_sel_hi:[1,0,1]
	v_mad_i64_i32 v[18:19], s[0:1], v18, s3, v[6:7]
	s_waitcnt lgkmcnt(0)
	v_pk_fma_f32 v[28:29], v[32:33], v[70:71], v[28:29] op_sel_hi:[1,0,1]
	v_pk_fma_f32 v[26:27], v[30:31], v[70:71], v[26:27] op_sel_hi:[1,0,1]
	s_waitcnt vmcnt(5)
	v_pk_fma_f32 v[30:31], v[36:37], v[42:43], v[50:51] op_sel:[0,1,0]
	v_pk_fma_f32 v[32:33], v[34:35], v[42:43], v[52:53] op_sel:[0,1,0]
	v_pk_fma_f32 v[42:43], v[36:37], v[54:55], v[22:23] op_sel:[0,1,0]
	v_or_b32_e32 v22, 12, v13
	global_load_dwordx4 v[18:21], v[18:19], off nt
	v_pk_fma_f32 v[50:51], v[34:35], v[54:55], v[24:25] op_sel:[0,1,0]
	v_mad_i64_i32 v[22:23], s[0:1], v22, s3, v[6:7]
	v_pk_fma_f32 v[40:41], v[34:35], v[62:63], v[40:41] op_sel:[0,1,0]
	v_pk_fma_f32 v[34:35], v[34:35], v[70:71], v[26:27] op_sel:[0,1,0]
	v_or_b32_e32 v26, 13, v13
	global_load_dwordx4 v[22:25], v[22:23], off nt
	s_waitcnt vmcnt(6)
	v_pk_fma_f32 v[52:53], v[48:49], v[44:45], v[30:31] op_sel_hi:[1,0,1]
	v_mad_i64_i32 v[26:27], s[0:1], v26, s3, v[6:7]
	v_or_b32_e32 v30, 14, v13
	v_pk_fma_f32 v[38:39], v[36:37], v[62:63], v[38:39] op_sel:[0,1,0]
	v_pk_fma_f32 v[36:37], v[36:37], v[70:71], v[28:29] op_sel:[0,1,0]
	global_load_dwordx4 v[26:29], v[26:27], off nt
	v_mad_i64_i32 v[30:31], s[0:1], v30, s3, v[6:7]
	v_or_b32_e32 v13, 15, v13
	v_pk_fma_f32 v[54:55], v[46:47], v[44:45], v[32:33] op_sel_hi:[1,0,1]
	global_load_dwordx4 v[30:33], v[30:31], off nt
	v_mad_i64_i32 v[6:7], s[0:1], v13, s3, v[6:7]
	v_pk_fma_f32 v[42:43], v[48:49], v[56:57], v[42:43] op_sel_hi:[1,0,1]
	v_pk_fma_f32 v[50:51], v[46:47], v[56:57], v[50:51] op_sel_hi:[1,0,1]
	v_pk_fma_f32 v[58:59], v[48:49], v[64:65], v[38:39] op_sel_hi:[1,0,1]
	v_pk_fma_f32 v[60:61], v[46:47], v[64:65], v[40:41] op_sel_hi:[1,0,1]
	v_pk_fma_f32 v[62:63], v[48:49], v[72:73], v[36:37] op_sel_hi:[1,0,1]
	v_pk_fma_f32 v[66:67], v[46:47], v[72:73], v[34:35] op_sel_hi:[1,0,1]
	ds_read_b128 v[34:37], v89 offset:32
	ds_read_b128 v[38:41], v89 offset:48
	global_load_dwordx4 v[46:49], v[6:7], off nt
	v_mov_b32_e32 v44, v57
	s_waitcnt vmcnt(8)
	v_pk_fma_f32 v[68:69], v[76:77], v[44:45], v[42:43] op_sel_hi:[1,0,1]
	v_mov_b32_e32 v42, v65
	v_mov_b32_e32 v6, v45
	v_pk_fma_f32 v[82:83], v[76:77], v[42:43], v[58:59] op_sel_hi:[1,0,1]
	v_pk_fma_f32 v[84:85], v[74:75], v[42:43], v[60:61] op_sel_hi:[1,0,1]
	v_mov_b32_e32 v42, v73
	v_pk_fma_f32 v[52:53], v[76:77], v[6:7], v[52:53] op_sel_hi:[1,0,1]
	v_pk_fma_f32 v[6:7], v[74:75], v[6:7], v[54:55] op_sel_hi:[1,0,1]
	v_pk_fma_f32 v[70:71], v[74:75], v[44:45], v[50:51] op_sel_hi:[1,0,1]
	v_pk_fma_f32 v[72:73], v[76:77], v[42:43], v[62:63] op_sel_hi:[1,0,1]
	v_pk_fma_f32 v[74:75], v[74:75], v[42:43], v[66:67] op_sel_hi:[1,0,1]
	ds_read_b128 v[42:45], v89 offset:8224
	s_waitcnt vmcnt(7) lgkmcnt(2)
	v_pk_fma_f32 v[76:77], v[80:81], v[34:35], v[52:53] op_sel_hi:[1,0,1]
	ds_read_b128 v[50:53], v89 offset:16416
	ds_read_b128 v[54:57], v89 offset:8240
	ds_read_b128 v[58:61], v89 offset:24608
	ds_read_b128 v[62:65], v89 offset:16432
	v_pk_fma_f32 v[6:7], v[78:79], v[34:35], v[6:7] op_sel_hi:[1,0,1]
	s_waitcnt lgkmcnt(4)
	v_pk_fma_f32 v[86:87], v[80:81], v[42:43], v[68:69] op_sel_hi:[1,0,1]
	ds_read_b128 v[66:69], v89 offset:24624
	v_pk_fma_f32 v[70:71], v[78:79], v[42:43], v[70:71] op_sel_hi:[1,0,1]
	s_waitcnt lgkmcnt(4)
	v_pk_fma_f32 v[82:83], v[80:81], v[50:51], v[82:83] op_sel_hi:[1,0,1]
	v_pk_fma_f32 v[84:85], v[78:79], v[50:51], v[84:85] op_sel_hi:[1,0,1]
	s_waitcnt lgkmcnt(2)
	v_pk_fma_f32 v[74:75], v[78:79], v[58:59], v[74:75] op_sel_hi:[1,0,1]
	v_pk_fma_f32 v[72:73], v[80:81], v[58:59], v[72:73] op_sel_hi:[1,0,1]
	s_waitcnt vmcnt(6)
	v_pk_fma_f32 v[76:77], v[2:3], v[34:35], v[76:77] op_sel:[0,1,0]
	v_pk_fma_f32 v[6:7], v[0:1], v[34:35], v[6:7] op_sel:[0,1,0]
	v_pk_fma_f32 v[34:35], v[2:3], v[42:43], v[86:87] op_sel:[0,1,0]
	v_pk_fma_f32 v[42:43], v[0:1], v[42:43], v[70:71] op_sel:[0,1,0]
	v_pk_fma_f32 v[70:71], v[2:3], v[50:51], v[82:83] op_sel:[0,1,0]
	v_pk_fma_f32 v[50:51], v[0:1], v[50:51], v[84:85] op_sel:[0,1,0]
	v_pk_fma_f32 v[0:1], v[0:1], v[58:59], v[74:75] op_sel:[0,1,0]
	v_pk_fma_f32 v[2:3], v[2:3], v[58:59], v[72:73] op_sel:[0,1,0]
	s_waitcnt vmcnt(5)
	v_pk_fma_f32 v[58:59], v[16:17], v[36:37], v[76:77] op_sel_hi:[1,0,1]
	v_pk_fma_f32 v[6:7], v[14:15], v[36:37], v[6:7] op_sel_hi:[1,0,1]
	v_pk_fma_f32 v[34:35], v[16:17], v[44:45], v[34:35] op_sel_hi:[1,0,1]
	v_pk_fma_f32 v[42:43], v[14:15], v[44:45], v[42:43] op_sel_hi:[1,0,1]
	v_pk_fma_f32 v[50:51], v[14:15], v[52:53], v[50:51] op_sel_hi:[1,0,1]
	v_pk_fma_f32 v[0:1], v[14:15], v[60:61], v[0:1] op_sel_hi:[1,0,1]
	v_mov_b32_e32 v14, v37
	v_mov_b32_e32 v44, v61
	v_pk_fma_f32 v[70:71], v[16:17], v[52:53], v[70:71] op_sel_hi:[1,0,1]
	v_pk_fma_f32 v[2:3], v[16:17], v[60:61], v[2:3] op_sel_hi:[1,0,1]
	v_mov_b32_e32 v36, v53
	s_waitcnt vmcnt(4)
	v_pk_fma_f32 v[16:17], v[20:21], v[14:15], v[58:59] op_sel_hi:[1,0,1]
	v_pk_fma_f32 v[6:7], v[18:19], v[14:15], v[6:7] op_sel_hi:[1,0,1]
	v_mov_b32_e32 v14, v45
	v_pk_fma_f32 v[0:1], v[18:19], v[44:45], v[0:1] op_sel_hi:[1,0,1]
	v_pk_fma_f32 v[34:35], v[20:21], v[14:15], v[34:35] op_sel_hi:[1,0,1]
	v_pk_fma_f32 v[14:15], v[18:19], v[14:15], v[42:43] op_sel_hi:[1,0,1]
	v_pk_fma_f32 v[42:43], v[20:21], v[36:37], v[70:71] op_sel_hi:[1,0,1]
	v_pk_fma_f32 v[36:37], v[18:19], v[36:37], v[50:51] op_sel_hi:[1,0,1]
	v_pk_fma_f32 v[2:3], v[20:21], v[44:45], v[2:3] op_sel_hi:[1,0,1]
	s_waitcnt vmcnt(3)
	v_pk_fma_f32 v[16:17], v[24:25], v[38:39], v[16:17] op_sel_hi:[1,0,1]
	v_pk_fma_f32 v[6:7], v[22:23], v[38:39], v[6:7] op_sel_hi:[1,0,1]
	s_waitcnt lgkmcnt(0)
	v_pk_fma_f32 v[0:1], v[22:23], v[66:67], v[0:1] op_sel_hi:[1,0,1]
	v_pk_fma_f32 v[18:19], v[24:25], v[54:55], v[34:35] op_sel_hi:[1,0,1]
	v_pk_fma_f32 v[14:15], v[22:23], v[54:55], v[14:15] op_sel_hi:[1,0,1]
	v_pk_fma_f32 v[34:35], v[22:23], v[62:63], v[36:37] op_sel_hi:[1,0,1]
	v_pk_fma_f32 v[2:3], v[24:25], v[66:67], v[2:3] op_sel_hi:[1,0,1]
	s_waitcnt vmcnt(2)
	v_pk_fma_f32 v[16:17], v[28:29], v[38:39], v[16:17] op_sel:[0,1,0]
	v_pk_fma_f32 v[6:7], v[26:27], v[38:39], v[6:7] op_sel:[0,1,0]
	v_pk_fma_f32 v[0:1], v[26:27], v[66:67], v[0:1] op_sel:[0,1,0]
	v_pk_fma_f32 v[20:21], v[24:25], v[62:63], v[42:43] op_sel_hi:[1,0,1]
	v_pk_fma_f32 v[18:19], v[28:29], v[54:55], v[18:19] op_sel:[0,1,0]
	v_pk_fma_f32 v[14:15], v[26:27], v[54:55], v[14:15] op_sel:[0,1,0]
	v_pk_fma_f32 v[22:23], v[26:27], v[62:63], v[34:35] op_sel:[0,1,0]
	v_pk_fma_f32 v[2:3], v[28:29], v[66:67], v[2:3] op_sel:[0,1,0]
	s_waitcnt vmcnt(1)
	v_pk_fma_f32 v[16:17], v[32:33], v[40:41], v[16:17] op_sel_hi:[1,0,1]
	v_pk_fma_f32 v[6:7], v[30:31], v[40:41], v[6:7] op_sel_hi:[1,0,1]
	v_pk_fma_f32 v[26:27], v[30:31], v[68:69], v[0:1] op_sel_hi:[1,0,1]
	v_mov_b32_e32 v0, v41
	v_pk_fma_f32 v[20:21], v[28:29], v[62:63], v[20:21] op_sel:[0,1,0]
	v_pk_fma_f32 v[18:19], v[32:33], v[56:57], v[18:19] op_sel_hi:[1,0,1]
	v_pk_fma_f32 v[14:15], v[30:31], v[56:57], v[14:15] op_sel_hi:[1,0,1]
	v_pk_fma_f32 v[24:25], v[32:33], v[68:69], v[2:3] op_sel_hi:[1,0,1]
	s_waitcnt vmcnt(0)
	v_pk_fma_f32 v[2:3], v[48:49], v[0:1], v[16:17] op_sel_hi:[1,0,1]
	v_pk_fma_f32 v[0:1], v[46:47], v[0:1], v[6:7] op_sel_hi:[1,0,1]
	v_mov_b32_e32 v6, v57
	v_pk_fma_f32 v[20:21], v[32:33], v[64:65], v[20:21] op_sel_hi:[1,0,1]
	v_pk_fma_f32 v[22:23], v[30:31], v[64:65], v[22:23] op_sel_hi:[1,0,1]
	v_pk_fma_f32 v[16:17], v[48:49], v[6:7], v[18:19] op_sel_hi:[1,0,1]
	v_pk_fma_f32 v[14:15], v[46:47], v[6:7], v[14:15] op_sel_hi:[1,0,1]
	v_mov_b32_e32 v6, v65
	v_pk_fma_f32 v[20:21], v[48:49], v[6:7], v[20:21] op_sel_hi:[1,0,1]
	v_pk_fma_f32 v[18:19], v[46:47], v[6:7], v[22:23] op_sel_hi:[1,0,1]
	v_mov_b32_e32 v6, v69
	v_pk_fma_f32 v[24:25], v[48:49], v[6:7], v[24:25] op_sel_hi:[1,0,1]
	v_pk_fma_f32 v[22:23], v[46:47], v[6:7], v[26:27] op_sel_hi:[1,0,1]
	ds_write_b128 v12, v[0:3] offset:32768
	ds_write_b128 v12, v[14:17] offset:33024
	ds_write_b128 v12, v[18:21] offset:33280
	ds_write_b128 v12, v[22:25] offset:33536
	s_add_i32 s100, s8, s34
	s_cmpk_lt_i32 s100, 0x300
	s_cbranch_scc0 .Lada_nopf
	s_mul_hi_i32 s0, s100, 0x2aaaaaab
	s_lshr_b32 s1, s0, 31
	s_ashr_i32 s99, s0, 5
	s_add_i32 s99, s99, s1
	s_mul_i32 s0, s99, 0xc0
	s_sub_i32 s0, s100, s0
	s_lshl_b32 s98, s0, 6
	v_or_b32_e32 v148, s98, v8
	v_ashrrev_i32_e32 v149, 31, v148
	v_lshl_add_u32 v13, s99, 9, v9
	v_lshl_add_u64 v[6:7], v[148:149], 2, s[22:23]
	v_mad_i64_i32 v[148:149], s[0:1], v13, s3, v[6:7]
	global_load_dwordx4 v[14:17], v[148:149], off nt
	v_or_b32_e32 v148, 1, v13
	v_mad_i64_i32 v[148:149], s[0:1], v148, s3, v[6:7]
	global_load_dwordx4 v[18:21], v[148:149], off nt
	v_or_b32_e32 v148, 2, v13
	v_mad_i64_i32 v[148:149], s[0:1], v148, s3, v[6:7]
	global_load_dwordx4 v[22:25], v[148:149], off nt
	v_or_b32_e32 v148, 3, v13
	v_mad_i64_i32 v[148:149], s[0:1], v148, s3, v[6:7]
	global_load_dwordx4 v[26:29], v[148:149], off nt
	v_or_b32_e32 v148, 4, v13
	v_mad_i64_i32 v[148:149], s[0:1], v148, s3, v[6:7]
	global_load_dwordx4 v[30:33], v[148:149], off nt
	v_or_b32_e32 v148, 5, v13
	v_mad_i64_i32 v[148:149], s[0:1], v148, s3, v[6:7]
	global_load_dwordx4 v[34:37], v[148:149], off nt
.Lada_nopf:
	s_waitcnt lgkmcnt(0)
	s_barrier
	s_and_saveexec_b64 s[6:7], vcc
	s_cbranch_execz .LBB0_24
	v_mov_b32_e32 v150, 0
	s_mov_b32 s0, 0
.LBB0_27:
	v_add_u32_e32 v151, s0, v11
	ds_read2st64_b32 v[152:153], v151 offset1:4
	ds_read2st64_b32 v[154:155], v151 offset0:8 offset1:12
	ds_read2st64_b32 v[156:157], v151 offset0:16 offset1:20
	ds_read2st64_b32 v[158:159], v151 offset0:24 offset1:28
	s_addk_i32 s0, 0x2000
	s_waitcnt lgkmcnt(3)
	v_add_f32_e32 v150, v150, v152
	v_add_f32_e32 v150, v150, v153
	s_waitcnt lgkmcnt(2)
	v_add_f32_e32 v150, v150, v154
	v_add_f32_e32 v150, v150, v155
	s_waitcnt lgkmcnt(1)
	v_add_f32_e32 v150, v150, v156
	v_add_f32_e32 v150, v150, v157
	s_waitcnt lgkmcnt(0)
	v_add_f32_e32 v150, v150, v158
	s_cmpk_eq_u32 s0, 0x8000
	v_add_f32_e32 v150, v150, v159
	s_cbranch_scc0 .LBB0_27
	v_lshl_add_u32 v151, s5, 2, v10
	v_mov_b64_e32 v[152:153], s[44:45]
	s_ashr_i32 s5, s4, 31
	v_mad_i64_i32 v[152:153], s[0:1], v151, s3, v[152:153]
	v_lshl_add_u64 v[152:153], s[4:5], 2, v[152:153]
	v_lshl_add_u64 v[152:153], v[152:153], 0, v[4:5]
	global_store_dword v[152:153], v150, off sc1
	s_branch .LBB0_24
